# dense-attn loop: K/V LDS-DMA addresses via SGPR base + 32-bit lane offset (no 64-bit VALU adds)
# speedup vs baseline: 1.0103x; 1.0103x over previous
; #define WAIT_BAR(N) asm volatile("s_waitcnt vmcnt(" #N ") lgkmcnt(0)\n\ts_barrier":::"memory")
;   #define DMA_K(t,slot) glds16(ksrc+(long)(t)*KVBLK*KP,(unsigned)__builtin_amdgcn_readfirstlane(kdst+(slot)))
;   #define DMA_V(t,slot) glds16(vsrc+(long)(t)*KVBLK*KP,(unsigned)__builtin_amdgcn_readfirstlane(vdst+(slot)))
;   #define CMASK(P0,P1,t) do{}while(0)
;   #define START(P0,P1) do{ _Pragma("unroll") for(int r=0;r<16;++r)P0[r]=__builtin_amdgcn_exp2f(P0[r]); }while(0)
; template<int THRL> __device__ __forceinline__ void attn_unit(int b,int h,int qb,const bf16*Q,const bf16*__restrict__ K,const bf16*__restrict__ V,bf16*O,float*gssrow,float mref,char*shm){
;   int tid_l=threadIdx.x; asm volatile("":"+v"(tid_l)); const int tid=tid_l,lane=tid&63,r32=lane&31,hi=lane>>5; const int wid=__builtin_amdgcn_readfirstlane(tid>>6);
;   const long rowbase=(long)b*SEQ; const int q0=qb*QB;
;   const bf16*Qw=Q+(rowbase+q0+wid*QBLK)*QP+h*D;
;   const int g=h/3; const bf16*Kh=K+rowbase*KP+g*D,*Vh=V+rowbase*KP+g*D;
;   const unsigned lds0=(unsigned)(uintptr_t)shm;
;   float*wsf=(float*)(shm+LDS_WS)+wid*64;
;   const bf16*ksrc=Kh+(long)lane*KP+wid*8;
;   const bf16*vsrc=Vh+(long)(16*(wid&3)+(lane>>2))*KP+(wid>>2)*32+(lane&3)*8;
;   const unsigned kdst=lds0+LDS_K+wid*1024, vdst=lds0+LDS_V+wid*1024;
;     ...
;   const int vb0=(int)(lds0+LDS_V)+((lane>>4)&1)*32+(lane&3)*8+(4*hi+((lane&15)>>2))*64;
;   const char*Kbase=shm+LDS_K; bf16x8 kf[8];
;   const lds_cptr shm3=(lds_cptr)shm; const lds_cptr kp0=shm3+LDS_K+hi*1024+r32*16; const lds_cptr vp0=shm3+LDS_V+((lane>>4)&1)*32+(lane&3)*8+(4*hi+((lane&15)>>2))*64;
;   const int NT=SEQ/KVBLK;
;   DMA_K(0,0);DMA_V(0,0);DMA_K(1,SLOTB);
;   bf16x8 qr[4];
;   #pragma unroll
;   for(int d0=0;d0<4;++d0)qr[d0]=*reinterpret_cast<const bf16x8*>(&Qw[(long)r32*QP+d0*16+hi*8]);
;   float l_reg=0.f;f32x16 o[2];o[0]=f32x16{};o[1]=f32x16{};f32x16 negm;_Pragma("unroll") for(int r=0;r<16;++r)negm[r]=-mref;asm volatile("":"+v"(negm));
;     ...
;   f32x16 pA0,pA1,pB0,pB1;
;   int sl_prev=0,sl_cur=0,sl_next=SLOTB;
;     ...
;   DMA_K(2,2*SLOTB);
;   WAIT_BAR(3);
;   qkt(pA0,pA1,Kbase,qr,negm,r32,hi);asm volatile("s_nop 15\n\ts_nop 7":"+v"(pA0),"+v"(pA1));CMASK(pA0,pA1,0);
;   START(pA0,pA1);
;   _Pragma("unroll") for(int r=0;r<16;++r)pA1[r]=__builtin_amdgcn_exp2f(pA1[r]);
;   WAIT_BAR(0);
;   DMA_K(3,0);DMA_V(1,SLOTB);
;   ROT();
;   kload8(kf,kp0+sl_cur);
.LBB0_449:
	s_lshl_b64 s[20:21], s[54:55], 1
	v_readlane_b32 s12, v254, 60
	s_add_u32 s20, s12, s20
	v_readlane_b32 s12, v254, 61
	s_addc_u32 s21, s12, s21
	s_add_u32 s20, s20, s50
	s_addc_u32 s21, s21, s51
	s_add_u32 s20, s20, s48
	v_exp_f32_e32 v48, v0
	v_lshlrev_b32_e32 v0, 1, v194
	s_addc_u32 s21, s21, s49
	v_and_b32_e32 v202, 32, v0
	v_lshlrev_b32_e32 v0, 4, v194
	v_lshl_add_u64 v[190:191], s[20:21], 0, v[128:129]
	s_lshl_b64 s[20:21], s[52:53], 1
	v_and_b32_e32 v0, 0xc0, v0
	s_add_u32 s20, s20, s50
	v_lshl_or_b32 v198, v197, 8, v0
	v_add_u32_e32 v0, 0, v202
	s_addc_u32 s21, s21, s51
	v_add3_u32 v199, v0, v201, v198
	v_and_b32_e32 v0, 3, v194
	s_add_u32 s20, s20, s48
	v_lshlrev_b32_e32 v128, 4, v0
	s_addc_u32 s21, s21, s49
	v_exp_f32_e32 v49, v1
	v_lshl_add_u64 v[0:1], s[20:21], 0, v[128:129]
	s_lshl_b32 s20, s15, 6
	v_exp_f32_e32 v64, v16
	v_exp_f32_e32 v65, v17
	v_exp_f32_e32 v66, v18
	v_exp_f32_e32 v67, v19
	v_exp_f32_e32 v68, v20
	v_exp_f32_e32 v69, v21
	v_exp_f32_e32 v70, v22
	v_exp_f32_e32 v71, v23
	v_exp_f32_e32 v72, v24
	v_exp_f32_e32 v73, v25
	v_exp_f32_e32 v74, v26
	v_exp_f32_e32 v75, v27
	v_exp_f32_e32 v76, v28
	v_exp_f32_e32 v77, v29
	v_exp_f32_e32 v78, v30
	v_exp_f32_e32 v79, v31
	v_exp_f32_e32 v50, v2
	v_exp_f32_e32 v51, v3
	v_exp_f32_e32 v52, v4
	v_exp_f32_e32 v53, v5
	v_exp_f32_e32 v54, v6
	v_exp_f32_e32 v55, v7
	v_exp_f32_e32 v56, v8
	v_exp_f32_e32 v57, v9
	v_exp_f32_e32 v58, v10
	v_exp_f32_e32 v59, v11
	v_exp_f32_e32 v60, v12
	v_exp_f32_e32 v61, v13
	v_exp_f32_e32 v62, v14
	v_exp_f32_e32 v63, v15
	s_and_b32 s20, s20, 0x3000
	v_lshl_or_b32 v128, v84, 8, s20
	v_readlane_b32 s12, v254, 62
	v_lshl_add_u64 v[0:1], v[0:1], 0, v[128:129]
	v_readlane_b32 s13, v254, 63
	v_mov_b32_e32 v203, 0
	s_movk_i32 s29, 0x4000
	v_lshl_add_u64 v[192:193], s[12:13], 0, v[0:1]
	s_movk_i32 s21, 0x2000
	s_mov_b32 s31, 0
	s_mov_b32 s20, -1
	v_mov_b32_e32 v0, 0
	v_mov_b32_e32 v1, v203
	v_mov_b32_e32 v2, v203
	v_mov_b32_e32 v3, v203
	v_mov_b32_e32 v4, v203
	v_mov_b32_e32 v5, v203
	v_mov_b32_e32 v6, v203
	v_mov_b32_e32 v7, v203
	v_mov_b32_e32 v8, v203
	v_mov_b32_e32 v9, v203
	v_mov_b32_e32 v10, v203
	v_mov_b32_e32 v11, v203
	v_mov_b32_e32 v12, v203
	v_mov_b32_e32 v13, v203
	v_mov_b32_e32 v14, v203
	v_mov_b32_e32 v15, v203
	v_mov_b32_e32 v16, 0
	v_mov_b32_e32 v17, v203
	v_mov_b32_e32 v18, v203
	v_mov_b32_e32 v19, v203
	v_mov_b32_e32 v20, v203
	v_mov_b32_e32 v21, v203
	v_mov_b32_e32 v22, v203
	v_mov_b32_e32 v23, v203
	v_mov_b32_e32 v24, v203
	v_mov_b32_e32 v25, v203
	v_mov_b32_e32 v26, v203
	v_mov_b32_e32 v27, v203
	v_mov_b32_e32 v28, v203
	v_mov_b32_e32 v29, v203
	v_mov_b32_e32 v30, v203
	v_mov_b32_e32 v31, v203
	v_readfirstlane_b32 s98, v190
	v_readfirstlane_b32 s99, v191
	v_readfirstlane_b32 s100, v192
	v_readfirstlane_b32 s101, v193
	v_subrev_u32_e32 v216, s98, v190
	v_subrev_u32_e32 v217, s100, v192
	v_add_u32_e32 v218, 0x10000, v216
	v_add_u32_e32 v216, 0xc000, v216
	v_add_u32_e32 v219, 0x8000, v217
	v_add_u32_e32 v217, 0x4000, v217
.LBB0_450:
	s_mov_b32 s30, s29
	s_mov_b32 s29, s21
	v_add_u32_e32 v128, s31, v199
	ds_read_b64_tr_b16 v[204:205], v128 offset:24576
	ds_read_b64_tr_b16 v[206:207], v128 offset:25088
	v_add_f32_e32 v84, v64, v65
	v_add_f32_e32 v84, v66, v84
	v_add_f32_e32 v84, v67, v84
	v_add_f32_e32 v84, v68, v84
	v_add_f32_e32 v84, v69, v84
	v_cvt_pk_bf16_f32 v154, v64, v65
	v_cvt_pk_bf16_f32 v155, v66, v67
	v_mfma_f32_32x32x16_bf16 v[96:111], v[80:83], v[158:161], v[32:47]
	ds_read_b64_tr_b16 v[64:65], v128 offset:28672
	ds_read_b64_tr_b16 v[66:67], v128 offset:29184
	v_add_f32_e32 v80, v70, v84
	v_add_f32_e32 v80, v71, v80
	v_add_f32_e32 v80, v72, v80
	v_add_f32_e32 v130, v73, v80
	v_mfma_f32_32x32x16_bf16 v[80:95], v[166:169], v[158:161], v[32:47]
	v_cvt_pk_bf16_f32 v156, v68, v69
	v_cvt_pk_bf16_f32 v157, v70, v71
	ds_read_b64_tr_b16 v[68:69], v128 offset:25600
	ds_read_b64_tr_b16 v[70:71], v128 offset:26112
	v_add_f32_e32 v130, v74, v130
	v_add_f32_e32 v130, v75, v130
	v_add_f32_e32 v130, v76, v130
	v_add_f32_e32 v130, v77, v130
	v_cvt_pk_bf16_f32 v146, v72, v73
	v_cvt_pk_bf16_f32 v147, v74, v75
	v_mfma_f32_32x32x16_bf16 v[96:111], v[170:173], v[150:153], v[96:111]
	ds_read_b64_tr_b16 v[72:73], v128 offset:29696
	ds_read_b64_tr_b16 v[74:75], v128 offset:30208
	v_mfma_f32_32x32x16_bf16 v[80:95], v[162:165], v[150:153], v[80:95]
	v_add_f32_e32 v130, v78, v130
	v_add_f32_e32 v130, v79, v130
	v_add_f32_e32 v130, v48, v130
	v_add_f32_e32 v130, v49, v130
	v_cvt_pk_bf16_f32 v148, v76, v77
	v_cvt_pk_bf16_f32 v149, v78, v79
	ds_read_b64_tr_b16 v[76:77], v128 offset:26624
	ds_read_b64_tr_b16 v[78:79], v128 offset:27136
	v_mfma_f32_32x32x16_bf16 v[96:111], v[124:127], v[142:145], v[96:111]
	v_add_f32_e32 v124, v50, v130
	v_add_f32_e32 v124, v51, v124
	v_add_f32_e32 v124, v52, v124
	v_add_f32_e32 v124, v53, v124
	v_cvt_pk_bf16_f32 v138, v48, v49
	v_cvt_pk_bf16_f32 v139, v50, v51
	ds_read_b64_tr_b16 v[48:49], v128 offset:30720
	ds_read_b64_tr_b16 v[50:51], v128 offset:31232
	v_mfma_f32_32x32x16_bf16 v[80:95], v[120:123], v[142:145], v[80:95]
	v_add_f32_e32 v120, v54, v124
	v_add_f32_e32 v120, v55, v120
	v_add_f32_e32 v120, v56, v120
	v_add_f32_e32 v120, v57, v120
	v_cvt_pk_bf16_f32 v140, v52, v53
	v_cvt_pk_bf16_f32 v141, v54, v55
	ds_read_b64_tr_b16 v[52:53], v128 offset:27648
	ds_read_b64_tr_b16 v[54:55], v128 offset:28160
	v_mfma_f32_32x32x16_bf16 v[96:111], v[116:119], v[134:137], v[96:111]
	v_add_f32_e32 v116, v58, v120
	v_add_f32_e32 v116, v59, v116
	v_add_f32_e32 v116, v60, v116
	v_add_f32_e32 v116, v61, v116
	v_cvt_pk_bf16_f32 v130, v56, v57
	v_cvt_pk_bf16_f32 v131, v58, v59
	ds_read_b64_tr_b16 v[56:57], v128 offset:31744
	ds_read_b64_tr_b16 v[58:59], v128 offset:32256
	v_mfma_f32_32x32x16_bf16 v[80:95], v[112:115], v[134:137], v[80:95]
	v_add_f32_e32 v112, v62, v116
	v_add_f32_e32 v112, v63, v112
	v_cvt_pk_bf16_f32 v132, v60, v61
	v_cvt_pk_bf16_f32 v133, v62, v63
	s_add_i32 m0, s21, s5
	s_nop 0
	global_load_lds_dwordx4 v216, s[98:99]
	s_add_i32 m0, s30, s4
	s_nop 0
	global_load_lds_dwordx4 v217, s[100:101]
	v_add_f32_e32 v128, v203, v112
	s_waitcnt lgkmcnt(14)
	v_mfma_f32_32x32x16_bf16 v[0:15], v[154:157], v[204:207], v[0:15]
	v_exp_f32_e32 v96, v96
	v_exp_f32_e32 v97, v97
	v_exp_f32_e32 v98, v98
	v_exp_f32_e32 v99, v99
	s_waitcnt lgkmcnt(12)
	v_mfma_f32_32x32x16_bf16 v[16:31], v[154:157], v[64:67], v[16:31]
	v_exp_f32_e32 v100, v100
	v_exp_f32_e32 v101, v101
	v_exp_f32_e32 v102, v102
	v_exp_f32_e32 v103, v103
	v_add_u32_e32 v64, s30, v200
	ds_read_b128 v[60:63], v64
	ds_read_b128 v[116:119], v64 offset:512
	s_waitcnt lgkmcnt(12)
	v_mfma_f32_32x32x16_bf16 v[0:15], v[146:149], v[68:71], v[0:15]
	v_exp_f32_e32 v104, v104
	v_exp_f32_e32 v105, v105
	v_exp_f32_e32 v106, v106
	v_exp_f32_e32 v107, v107
	ds_read_b128 v[120:123], v64 offset:2048
	ds_read_b128 v[124:127], v64 offset:2560
	s_waitcnt lgkmcnt(12)
	v_mfma_f32_32x32x16_bf16 v[16:31], v[146:149], v[72:75], v[16:31]
	v_exp_f32_e32 v108, v108
	v_exp_f32_e32 v109, v109
	v_exp_f32_e32 v110, v110
	v_exp_f32_e32 v111, v111
	ds_read_b128 v[162:165], v64 offset:4096
	ds_read_b128 v[166:169], v64 offset:4608
	s_waitcnt lgkmcnt(12)
	v_mfma_f32_32x32x16_bf16 v[0:15], v[138:141], v[76:79], v[0:15]
	v_exp_f32_e32 v80, v80
	v_exp_f32_e32 v81, v81
	v_exp_f32_e32 v82, v82
	v_exp_f32_e32 v83, v83
	ds_read_b128 v[170:173], v64 offset:6144
	ds_read_b128 v[112:115], v64 offset:6656
	s_waitcnt lgkmcnt(12)
	v_mfma_f32_32x32x16_bf16 v[16:31], v[138:141], v[48:51], v[16:31]
	v_exp_f32_e32 v84, v84
	v_exp_f32_e32 v85, v85
	v_exp_f32_e32 v86, v86
	v_exp_f32_e32 v87, v87
	s_waitcnt lgkmcnt(10)
	v_mfma_f32_32x32x16_bf16 v[0:15], v[130:133], v[52:55], v[0:15]
	v_exp_f32_e32 v88, v88
	v_exp_f32_e32 v89, v89
	v_exp_f32_e32 v90, v90
	v_exp_f32_e32 v91, v91
	s_waitcnt lgkmcnt(8)
	v_mfma_f32_32x32x16_bf16 v[16:31], v[130:133], v[56:59], v[16:31]
	v_exp_f32_e32 v92, v92
	v_exp_f32_e32 v93, v93
	v_exp_f32_e32 v94, v94
	v_exp_f32_e32 v95, v95
	s_waitcnt vmcnt(2) lgkmcnt(0)
	s_barrier
	s_add_i32 s21, s30, 0x2000
	s_cmpk_lg_i32 s30, 0x4000
	s_cselect_b32 s21, s21, 0
	v_add_u32_e32 v174, s29, v199
	ds_read_b64_tr_b16 v[204:205], v174 offset:24576
	ds_read_b64_tr_b16 v[206:207], v174 offset:25088
	v_mfma_f32_32x32x16_bf16 v[64:79], v[60:63], v[158:161], v[32:47]
	v_add_f32_e32 v48, v96, v97
	v_add_f32_e32 v48, v98, v48
	v_add_f32_e32 v48, v99, v48
	v_add_f32_e32 v48, v100, v48
	v_add_f32_e32 v48, v101, v48
	v_cvt_pk_bf16_f32 v154, v96, v97
	v_cvt_pk_bf16_f32 v155, v98, v99
	ds_read_b64_tr_b16 v[96:97], v174 offset:28672
	ds_read_b64_tr_b16 v[98:99], v174 offset:29184
	v_add_f32_e32 v48, v102, v48
	v_add_f32_e32 v48, v103, v48
	v_add_f32_e32 v48, v104, v48
	v_add_f32_e32 v130, v105, v48
	v_mfma_f32_32x32x16_bf16 v[48:63], v[116:119], v[158:161], v[32:47]
	v_cvt_pk_bf16_f32 v156, v100, v101
	v_cvt_pk_bf16_f32 v157, v102, v103
	ds_read_b64_tr_b16 v[100:101], v174 offset:25600
	ds_read_b64_tr_b16 v[102:103], v174 offset:26112
	v_mfma_f32_32x32x16_bf16 v[64:79], v[120:123], v[150:153], v[64:79]
	v_add_f32_e32 v116, v106, v130
	v_add_f32_e32 v116, v107, v116
	v_add_f32_e32 v116, v108, v116
	v_add_f32_e32 v116, v109, v116
	v_cvt_pk_bf16_f32 v146, v104, v105
	v_cvt_pk_bf16_f32 v147, v106, v107
	ds_read_b64_tr_b16 v[104:105], v174 offset:29696
	ds_read_b64_tr_b16 v[106:107], v174 offset:30208
	v_mfma_f32_32x32x16_bf16 v[48:63], v[124:127], v[150:153], v[48:63]
	v_add_f32_e32 v116, v110, v116
	v_add_f32_e32 v116, v111, v116
	v_add_f32_e32 v116, v80, v116
	v_add_f32_e32 v116, v81, v116
	v_cvt_pk_bf16_f32 v148, v108, v109
	v_cvt_pk_bf16_f32 v149, v110, v111
	ds_read_b64_tr_b16 v[108:109], v174 offset:26624
	ds_read_b64_tr_b16 v[110:111], v174 offset:27136
	v_mfma_f32_32x32x16_bf16 v[64:79], v[162:165], v[142:145], v[64:79]
	v_add_f32_e32 v116, v82, v116
	v_add_f32_e32 v116, v83, v116
	v_add_f32_e32 v116, v84, v116
	v_add_f32_e32 v116, v85, v116
	v_cvt_pk_bf16_f32 v138, v80, v81
	v_cvt_pk_bf16_f32 v139, v82, v83
	ds_read_b64_tr_b16 v[208:209], v174 offset:30720
	ds_read_b64_tr_b16 v[210:211], v174 offset:31232
	v_mfma_f32_32x32x16_bf16 v[48:63], v[166:169], v[142:145], v[48:63]
	v_add_f32_e32 v80, v86, v116
	v_add_f32_e32 v80, v87, v80
	v_add_f32_e32 v80, v88, v80
	v_add_f32_e32 v80, v89, v80
	v_cvt_pk_bf16_f32 v140, v84, v85
	v_cvt_pk_bf16_f32 v141, v86, v87
	ds_read_b64_tr_b16 v[84:85], v174 offset:27648
	ds_read_b64_tr_b16 v[86:87], v174 offset:28160
	v_mfma_f32_32x32x16_bf16 v[64:79], v[170:173], v[134:137], v[64:79]
	v_add_f32_e32 v80, v90, v80
	v_add_f32_e32 v80, v91, v80
	v_add_f32_e32 v80, v92, v80
	v_add_f32_e32 v80, v93, v80
	v_cvt_pk_bf16_f32 v130, v88, v89
	v_cvt_pk_bf16_f32 v131, v90, v91
	ds_read_b64_tr_b16 v[88:89], v174 offset:31744
	ds_read_b64_tr_b16 v[90:91], v174 offset:32256
	v_mfma_f32_32x32x16_bf16 v[48:63], v[112:115], v[134:137], v[48:63]
	v_add_f32_e32 v80, v94, v80
	v_add_f32_e32 v80, v95, v80
	v_cvt_pk_bf16_f32 v132, v92, v93
	v_cvt_pk_bf16_f32 v133, v94, v95
	s_mov_b64 s[48:49], 0x10000
	v_add_f32_e32 v203, v128, v80
	s_add_i32 m0, s30, s5
	s_nop 0
	global_load_lds_dwordx4 v218, s[98:99]
	s_add_i32 m0, s21, s4
	s_nop 0
	global_load_lds_dwordx4 v219, s[100:101]
	s_waitcnt lgkmcnt(14)
	v_mfma_f32_32x32x16_bf16 v[0:15], v[154:157], v[204:207], v[0:15]
	v_exp_f32_e32 v64, v64
	v_exp_f32_e32 v65, v65
	v_exp_f32_e32 v66, v66
	v_exp_f32_e32 v67, v67
	s_waitcnt lgkmcnt(12)
	v_mfma_f32_32x32x16_bf16 v[16:31], v[154:157], v[96:99], v[16:31]
	v_exp_f32_e32 v68, v68
	v_exp_f32_e32 v69, v69
	v_exp_f32_e32 v70, v70
	v_exp_f32_e32 v71, v71
	v_add_u32_e32 v92, s21, v200
	ds_read_b128 v[80:83], v92
	ds_read_b128 v[166:169], v92 offset:512
	s_waitcnt lgkmcnt(12)
	v_mfma_f32_32x32x16_bf16 v[0:15], v[146:149], v[100:103], v[0:15]
	v_exp_f32_e32 v72, v72
	v_exp_f32_e32 v73, v73
	v_exp_f32_e32 v74, v74
	v_exp_f32_e32 v75, v75
	ds_read_b128 v[170:173], v92 offset:2048
	ds_read_b128 v[162:165], v92 offset:2560
	s_waitcnt lgkmcnt(12)
	v_mfma_f32_32x32x16_bf16 v[16:31], v[146:149], v[104:107], v[16:31]
	v_exp_f32_e32 v76, v76
	v_exp_f32_e32 v77, v77
	v_exp_f32_e32 v78, v78
	v_exp_f32_e32 v79, v79
	ds_read_b128 v[124:127], v92 offset:4096
	ds_read_b128 v[120:123], v92 offset:4608
	s_waitcnt lgkmcnt(12)
	v_mfma_f32_32x32x16_bf16 v[0:15], v[138:141], v[108:111], v[0:15]
	v_exp_f32_e32 v48, v48
	v_exp_f32_e32 v49, v49
	v_exp_f32_e32 v50, v50
	v_exp_f32_e32 v51, v51
	ds_read_b128 v[116:119], v92 offset:6144
	ds_read_b128 v[112:115], v92 offset:6656
	s_waitcnt lgkmcnt(12)
	v_mfma_f32_32x32x16_bf16 v[16:31], v[138:141], v[208:211], v[16:31]
	v_exp_f32_e32 v52, v52
	v_exp_f32_e32 v53, v53
	v_exp_f32_e32 v54, v54
	v_exp_f32_e32 v55, v55
	s_waitcnt lgkmcnt(10)
	v_mfma_f32_32x32x16_bf16 v[0:15], v[130:133], v[84:87], v[0:15]
	v_exp_f32_e32 v56, v56
	v_exp_f32_e32 v57, v57
	v_exp_f32_e32 v58, v58
	v_exp_f32_e32 v59, v59
	s_waitcnt lgkmcnt(8)
	v_mfma_f32_32x32x16_bf16 v[16:31], v[130:133], v[88:91], v[16:31]
	v_exp_f32_e32 v60, v60
	v_exp_f32_e32 v61, v61
	v_exp_f32_e32 v62, v62
	v_exp_f32_e32 v63, v63
	s_add_i32 s29, s21, 0x2000
	s_waitcnt vmcnt(2) lgkmcnt(0)
	s_barrier
; #define WAIT_BAR(N) asm volatile("s_waitcnt vmcnt(" #N ") lgkmcnt(0)\n\ts_barrier":::"memory")
;   #define RESC() do{}while(0)
;   #define ROT() do{sl_prev=sl_cur;sl_cur=sl_next;sl_next=(sl_next==(NSLOT-1)*SLOTB)?0:sl_next+SLOTB;}while(0)
;   #define ENDW(tt) do{ if((tt)+3<NT){WAIT_BAR(2);} else if((tt)+2<NT){WAIT_BAR(1);} else {WAIT_BAR(0);} }while(0)
; template<int THRL> __device__ __forceinline__ void attn_unit(int b,int h,int qb,const bf16*Q,const bf16*__restrict__ K,const bf16*__restrict__ V,bf16*O,float*gssrow,float mref,char*shm){
;     ...
;   for(;t+5<NT;t+=2){
;     STEP(pB0,pB1,pA0,pA1,t,true,true,true);     WAIT_BAR(2); RESC(); ROT();
;     STEP(pA0,pA1,pB0,pB1,t+1,true,true,true);   WAIT_BAR(2); RESC(); ROT();
;   }
;     ...
;   for(;t+1<NT;t+=2){
;     STEP(pB0,pB1,pA0,pA1,t,(t+3<NT),(t+1<NT),(t+1<NT));       ENDW(t);   RESC(); ROT();
	s_add_u32 s98, s98, 0x8000
	s_addc_u32 s99, s99, 0
	s_add_u32 s100, s100, 0x8000
	s_addc_u32 s101, s101, 0
	s_cmpk_lg_i32 s21, 0x4000
	s_cselect_b32 s29, s29, 0
	s_add_i32 s20, s20, 2
	s_cmpk_gt_u32 s20, 0xf8
	s_mov_b32 s31, s30
	s_cbranch_scc0 .LBB0_450
	s_and_b32 s15, s15, 0x3fffffc0
	s_cmp_lg_u32 0, -1
	s_cselect_b32 s20, 0, 0
	s_lshl_b32 s15, s15, 2
	s_addk_i32 s20, 0x6000
	s_add_i32 s15, s15, 0
	v_add3_u32 v128, v202, s20, v201
	v_add_u32_e32 v174, s30, v199
	ds_read_b64_tr_b16 v[190:191], v174 offset:24576
	ds_read_b64_tr_b16 v[192:193], v174 offset:25088
	v_add_f32_e32 v84, v64, v65
	v_add_f32_e32 v84, v66, v84
	v_add_f32_e32 v84, v67, v84
	v_add_f32_e32 v84, v68, v84
	v_add_f32_e32 v84, v69, v84
	v_cvt_pk_bf16_f32 v154, v64, v65
	v_cvt_pk_bf16_f32 v155, v66, v67
	s_waitcnt lgkmcnt(9)
	v_mfma_f32_32x32x16_bf16 v[96:111], v[80:83], v[158:161], v[32:47]
	ds_read_b64_tr_b16 v[64:65], v174 offset:28672
	ds_read_b64_tr_b16 v[66:67], v174 offset:29184
	v_add_f32_e32 v80, v70, v84
	v_add_f32_e32 v80, v71, v80
	v_add_f32_e32 v80, v72, v80
	v_add_f32_e32 v130, v73, v80
	v_cvt_pk_bf16_f32 v156, v68, v69
	v_cvt_pk_bf16_f32 v157, v70, v71
	s_waitcnt lgkmcnt(10)
	v_mfma_f32_32x32x16_bf16 v[80:95], v[166:169], v[158:161], v[32:47]
	ds_read_b64_tr_b16 v[68:69], v174 offset:25600
	ds_read_b64_tr_b16 v[70:71], v174 offset:26112
	v_add_f32_e32 v130, v74, v130
	v_add_f32_e32 v130, v75, v130
	v_add_f32_e32 v130, v76, v130
	v_add_f32_e32 v130, v77, v130
	v_cvt_pk_bf16_f32 v146, v72, v73
	v_cvt_pk_bf16_f32 v147, v74, v75
	s_waitcnt lgkmcnt(11)
	v_mfma_f32_32x32x16_bf16 v[96:111], v[170:173], v[150:153], v[96:111]
	ds_read_b64_tr_b16 v[72:73], v174 offset:29696
	ds_read_b64_tr_b16 v[74:75], v174 offset:30208
	v_add_f32_e32 v130, v78, v130
	v_add_f32_e32 v130, v79, v130
	v_add_f32_e32 v130, v48, v130
	v_add_f32_e32 v130, v49, v130
	v_cvt_pk_bf16_f32 v148, v76, v77
	v_cvt_pk_bf16_f32 v149, v78, v79
	s_waitcnt lgkmcnt(12)
	v_mfma_f32_32x32x16_bf16 v[80:95], v[162:165], v[150:153], v[80:95]
	ds_read_b64_tr_b16 v[76:77], v174 offset:26624
	ds_read_b64_tr_b16 v[78:79], v174 offset:27136
	s_waitcnt lgkmcnt(13)
	v_mfma_f32_32x32x16_bf16 v[96:111], v[124:127], v[142:145], v[96:111]
	v_add_f32_e32 v124, v50, v130
	v_add_f32_e32 v124, v51, v124
	v_add_f32_e32 v124, v52, v124
	v_add_f32_e32 v124, v53, v124
	v_cvt_pk_bf16_f32 v138, v48, v49
	v_cvt_pk_bf16_f32 v139, v50, v51
	ds_read_b64_tr_b16 v[48:49], v174 offset:30720
	ds_read_b64_tr_b16 v[50:51], v174 offset:31232
	s_waitcnt lgkmcnt(14)
	v_mfma_f32_32x32x16_bf16 v[80:95], v[120:123], v[142:145], v[80:95]
	v_add_f32_e32 v120, v54, v124
	v_add_f32_e32 v120, v55, v120
	v_add_f32_e32 v120, v56, v120
	v_add_f32_e32 v120, v57, v120
	v_cvt_pk_bf16_f32 v140, v52, v53
	v_cvt_pk_bf16_f32 v141, v54, v55
	ds_read_b64_tr_b16 v[52:53], v174 offset:27648
	ds_read_b64_tr_b16 v[54:55], v174 offset:28160
	s_waitcnt lgkmcnt(14)
	v_mfma_f32_32x32x16_bf16 v[96:111], v[116:119], v[134:137], v[96:111]
	v_add_f32_e32 v116, v58, v120
	v_add_f32_e32 v116, v59, v116
	v_add_f32_e32 v116, v60, v116
	v_add_f32_e32 v116, v61, v116
	v_cvt_pk_bf16_f32 v130, v56, v57
	v_cvt_pk_bf16_f32 v131, v58, v59
	ds_read_b64_tr_b16 v[56:57], v174 offset:31744
	ds_read_b64_tr_b16 v[58:59], v174 offset:32256
	v_mfma_f32_32x32x16_bf16 v[80:95], v[112:115], v[134:137], v[80:95]
	v_add_f32_e32 v112, v62, v116
	v_add_f32_e32 v112, v63, v112
	v_add_f32_e32 v112, 0, v112
	v_cvt_pk_bf16_f32 v132, v60, v61
	v_cvt_pk_bf16_f32 v133, v62, v63
	s_mov_b64 s[12:13], 0x3f8000
	s_add_i32 s20, s21, s5
	v_lshl_add_u64 v[60:61], v[188:189], 0, s[12:13]
	s_mov_b32 s30, m0
	s_mov_b32 m0, s20
	s_nop 0
	global_load_lds_dwordx4 v[60:61], off
	s_mov_b32 m0, s30
	s_mov_b64 s[30:31], 0x3f0000
	v_lshl_add_u64 v[60:61], v[186:187], 0, s[30:31]
	s_add_i32 s20, s29, s4
	s_mov_b32 s30, m0
	s_mov_b32 m0, s20
	s_nop 0
	global_load_lds_dwordx4 v[60:61], off
	s_mov_b32 m0, s30
	v_add_f32_e32 v174, v203, v112
	s_waitcnt lgkmcnt(14)
	v_mfma_f32_32x32x16_bf16 v[0:15], v[154:157], v[190:193], v[0:15]
	v_exp_f32_e32 v96, v96
	v_exp_f32_e32 v97, v97
	v_exp_f32_e32 v98, v98
	v_exp_f32_e32 v99, v99
	s_waitcnt lgkmcnt(12)
	v_mfma_f32_32x32x16_bf16 v[16:31], v[154:157], v[64:67], v[16:31]
	v_exp_f32_e32 v100, v100
	v_exp_f32_e32 v101, v101
	v_exp_f32_e32 v102, v102
	v_exp_f32_e32 v103, v103
	v_add_u32_e32 v64, s29, v200
	ds_read_b128 v[60:63], v64
	ds_read_b128 v[162:165], v64 offset:512
	s_waitcnt lgkmcnt(12)
	v_mfma_f32_32x32x16_bf16 v[0:15], v[146:149], v[68:71], v[0:15]
	v_exp_f32_e32 v104, v104
	v_exp_f32_e32 v105, v105
	v_exp_f32_e32 v106, v106
	v_exp_f32_e32 v107, v107
	ds_read_b128 v[68:71], v64 offset:2048
	ds_read_b128 v[166:169], v64 offset:2560
	s_waitcnt lgkmcnt(12)
	v_mfma_f32_32x32x16_bf16 v[16:31], v[146:149], v[72:75], v[16:31]
	v_exp_f32_e32 v108, v108
	v_exp_f32_e32 v109, v109
	v_exp_f32_e32 v110, v110
	v_exp_f32_e32 v111, v111
	ds_read_b128 v[72:75], v64 offset:4096
	ds_read_b128 v[170:173], v64 offset:4608
	s_waitcnt lgkmcnt(12)
	v_mfma_f32_32x32x16_bf16 v[0:15], v[138:141], v[76:79], v[0:15]
	v_exp_f32_e32 v80, v80
	v_exp_f32_e32 v81, v81
	v_exp_f32_e32 v82, v82
	v_exp_f32_e32 v83, v83
	ds_read_b128 v[76:79], v64 offset:6144
	ds_read_b128 v[64:67], v64 offset:6656
	s_waitcnt lgkmcnt(12)
	v_mfma_f32_32x32x16_bf16 v[16:31], v[138:141], v[48:51], v[16:31]
	v_exp_f32_e32 v84, v84
	v_exp_f32_e32 v85, v85
	v_exp_f32_e32 v86, v86
	v_exp_f32_e32 v87, v87
	s_waitcnt lgkmcnt(10)
	v_mfma_f32_32x32x16_bf16 v[0:15], v[130:133], v[52:55], v[0:15]
	v_exp_f32_e32 v88, v88
	v_exp_f32_e32 v89, v89
	v_exp_f32_e32 v90, v90
	v_exp_f32_e32 v91, v91
	s_waitcnt lgkmcnt(8)
	v_mfma_f32_32x32x16_bf16 v[16:31], v[130:133], v[56:59], v[16:31]
	v_exp_f32_e32 v92, v92
	v_exp_f32_e32 v93, v93
	v_exp_f32_e32 v94, v94
	v_exp_f32_e32 v95, v95
	s_waitcnt vmcnt(2) lgkmcnt(0)
	s_barrier
;   #define RESC() do{}while(0)
;   #define ROT() do{sl_prev=sl_cur;sl_cur=sl_next;sl_next=(sl_next==(NSLOT-1)*SLOTB)?0:sl_next+SLOTB;}while(0)
;   #define ENDW(tt) do{ if((tt)+3<NT){WAIT_BAR(2);} else if((tt)+2<NT){WAIT_BAR(1);} else {WAIT_BAR(0);} }while(0)
; template<int THRL> __device__ __forceinline__ void attn_unit(int b,int h,int qb,const bf16*Q,const bf16*__restrict__ K,const bf16*__restrict__ V,bf16*O,float*gssrow,float mref,char*shm){
;     ...
;   for(;t+1<NT;t+=2){
;     STEP(pB0,pB1,pA0,pA1,t,(t+3<NT),(t+1<NT),(t+1<NT));       ENDW(t);   RESC(); ROT();
;     STEP(pA0,pA1,pB0,pB1,t+1,(t+4<NT),(t+2<NT),(t+2<NT));     ENDW(t+1); RESC(); ROT();
	s_add_i32 s20, s29, 0x2000
	s_cmpk_lg_i32 s29, 0x4000
	s_cselect_b32 s20, s20, 0
	v_add_u32_e32 v175, s21, v199
	ds_read_b64_tr_b16 v[190:191], v175 offset:24576
	ds_read_b64_tr_b16 v[192:193], v175 offset:25088
	v_add_f32_e32 v48, v96, v97
	v_add_f32_e32 v48, v98, v48
	v_add_f32_e32 v48, v99, v48
	v_add_f32_e32 v48, v100, v48
	v_add_f32_e32 v48, v101, v48
	v_cvt_pk_bf16_f32 v154, v96, v97
	v_cvt_pk_bf16_f32 v155, v98, v99
	s_waitcnt lgkmcnt(9)
	v_mfma_f32_32x32x16_bf16 v[112:127], v[60:63], v[158:161], v[32:47]
	ds_read_b64_tr_b16 v[96:97], v175 offset:28672
	ds_read_b64_tr_b16 v[98:99], v175 offset:29184
	v_add_f32_e32 v48, v102, v48
	v_add_f32_e32 v48, v103, v48
	v_add_f32_e32 v48, v104, v48
	v_add_f32_e32 v130, v105, v48
	s_waitcnt lgkmcnt(10)
	v_mfma_f32_32x32x16_bf16 v[48:63], v[162:165], v[158:161], v[32:47]
	v_cvt_pk_bf16_f32 v156, v100, v101
	v_cvt_pk_bf16_f32 v157, v102, v103
	ds_read_b64_tr_b16 v[100:101], v175 offset:25600
	ds_read_b64_tr_b16 v[102:103], v175 offset:26112
	s_waitcnt lgkmcnt(11)
	v_mfma_f32_32x32x16_bf16 v[112:127], v[68:71], v[150:153], v[112:127]
	v_add_f32_e32 v68, v106, v130
	v_add_f32_e32 v68, v107, v68
	v_add_f32_e32 v68, v108, v68
	v_add_f32_e32 v130, v109, v68
	v_cvt_pk_bf16_f32 v146, v104, v105
	v_cvt_pk_bf16_f32 v147, v106, v107
	ds_read_b64_tr_b16 v[68:69], v175 offset:29696
	ds_read_b64_tr_b16 v[70:71], v175 offset:30208
	s_waitcnt lgkmcnt(12)
	v_mfma_f32_32x32x16_bf16 v[48:63], v[166:169], v[150:153], v[48:63]
	v_add_f32_e32 v104, v110, v130
	v_add_f32_e32 v104, v111, v104
	v_add_f32_e32 v104, v80, v104
	v_add_f32_e32 v130, v81, v104
	v_cvt_pk_bf16_f32 v148, v108, v109
	v_cvt_pk_bf16_f32 v149, v110, v111
	ds_read_b64_tr_b16 v[104:105], v175 offset:26624
	ds_read_b64_tr_b16 v[106:107], v175 offset:27136
	s_waitcnt lgkmcnt(13)
	v_mfma_f32_32x32x16_bf16 v[112:127], v[72:75], v[142:145], v[112:127]
	v_add_f32_e32 v72, v82, v130
	v_add_f32_e32 v72, v83, v72
	v_add_f32_e32 v72, v84, v72
	v_add_f32_e32 v108, v85, v72
	v_cvt_pk_bf16_f32 v138, v80, v81
	v_cvt_pk_bf16_f32 v139, v82, v83
	ds_read_b64_tr_b16 v[72:73], v175 offset:30720
	ds_read_b64_tr_b16 v[74:75], v175 offset:31232
	s_waitcnt lgkmcnt(14)
	v_mfma_f32_32x32x16_bf16 v[48:63], v[170:173], v[142:145], v[48:63]
	v_add_f32_e32 v80, v86, v108
	v_add_f32_e32 v80, v87, v80
	v_add_f32_e32 v80, v88, v80
	v_add_f32_e32 v80, v89, v80
	v_cvt_pk_bf16_f32 v140, v84, v85
	v_cvt_pk_bf16_f32 v141, v86, v87
	ds_read_b64_tr_b16 v[84:85], v175 offset:27648
	ds_read_b64_tr_b16 v[86:87], v175 offset:28160
	s_waitcnt lgkmcnt(14)
	v_mfma_f32_32x32x16_bf16 v[112:127], v[76:79], v[134:137], v[112:127]
	v_add_f32_e32 v76, v90, v80
	v_add_f32_e32 v76, v91, v76
	v_add_f32_e32 v76, v92, v76
	v_add_f32_e32 v80, v93, v76
	v_cvt_pk_bf16_f32 v130, v88, v89
	v_cvt_pk_bf16_f32 v131, v90, v91
	ds_read_b64_tr_b16 v[76:77], v175 offset:31744
	ds_read_b64_tr_b16 v[78:79], v175 offset:32256
	v_mfma_f32_32x32x16_bf16 v[48:63], v[64:67], v[134:137], v[48:63]
	v_add_f32_e32 v64, v94, v80
	v_add_f32_e32 v64, v95, v64
	v_add_f32_e32 v64, 0, v64
	v_cvt_pk_bf16_f32 v132, v92, v93
	v_cvt_pk_bf16_f32 v133, v94, v95
	s_mov_b64 s[48:49], 0x3fc000
	v_add_f32_e32 v174, v174, v64
	s_add_i32 s5, s29, s5
	v_lshl_add_u64 v[64:65], v[188:189], 0, s[48:49]
	s_mov_b32 s21, m0
	s_mov_b32 m0, s5
	s_nop 0
	global_load_lds_dwordx4 v[64:65], off
	s_mov_b32 m0, s21
	s_mov_b64 s[30:31], 0x3f4000
	s_add_i32 s5, s20, s4
	v_lshl_add_u64 v[64:65], v[186:187], 0, s[30:31]
	s_mov_b32 s21, m0
	s_mov_b32 m0, s5
	s_nop 0
	global_load_lds_dwordx4 v[64:65], off
	s_mov_b32 m0, s21
	s_waitcnt lgkmcnt(14)
	v_mfma_f32_32x32x16_bf16 v[0:15], v[154:157], v[190:193], v[0:15]
	v_exp_f32_e32 v112, v112
	v_exp_f32_e32 v113, v113
	v_exp_f32_e32 v114, v114
	v_exp_f32_e32 v115, v115
	s_waitcnt lgkmcnt(12)
	v_mfma_f32_32x32x16_bf16 v[16:31], v[154:157], v[96:99], v[16:31]
	v_exp_f32_e32 v116, v116
	v_exp_f32_e32 v117, v117
	v_exp_f32_e32 v118, v118
	v_exp_f32_e32 v119, v119
	v_add_u32_e32 v80, s20, v200
	ds_read_b128 v[64:67], v80
	ds_read_b128 v[88:91], v80 offset:512
	s_waitcnt lgkmcnt(12)
	v_mfma_f32_32x32x16_bf16 v[0:15], v[146:149], v[100:103], v[0:15]
	v_exp_f32_e32 v120, v120
	v_exp_f32_e32 v121, v121
	v_exp_f32_e32 v122, v122
	v_exp_f32_e32 v123, v123
	ds_read_b128 v[92:95], v80 offset:2048
	ds_read_b128 v[162:165], v80 offset:2560
	s_waitcnt lgkmcnt(12)
	v_mfma_f32_32x32x16_bf16 v[16:31], v[146:149], v[68:71], v[16:31]
	v_exp_f32_e32 v124, v124
	v_exp_f32_e32 v125, v125
	v_exp_f32_e32 v126, v126
	v_exp_f32_e32 v127, v127
	ds_read_b128 v[166:169], v80 offset:4096
	ds_read_b128 v[170:173], v80 offset:4608
	s_waitcnt lgkmcnt(12)
	v_mfma_f32_32x32x16_bf16 v[0:15], v[138:141], v[104:107], v[0:15]
	v_exp_f32_e32 v48, v48
	v_exp_f32_e32 v49, v49
	v_exp_f32_e32 v50, v50
	v_exp_f32_e32 v51, v51
	ds_read_b128 v[188:191], v80 offset:6144
	ds_read_b128 v[80:83], v80 offset:6656
	s_waitcnt lgkmcnt(12)
	v_mfma_f32_32x32x16_bf16 v[16:31], v[138:141], v[72:75], v[16:31]
	v_exp_f32_e32 v52, v52
	v_exp_f32_e32 v53, v53
	v_exp_f32_e32 v54, v54
	v_exp_f32_e32 v55, v55
	s_waitcnt lgkmcnt(10)
	v_mfma_f32_32x32x16_bf16 v[0:15], v[130:133], v[84:87], v[0:15]
	v_exp_f32_e32 v56, v56
	v_exp_f32_e32 v57, v57
	v_exp_f32_e32 v58, v58
	v_exp_f32_e32 v59, v59
	s_waitcnt lgkmcnt(8)
	v_mfma_f32_32x32x16_bf16 v[16:31], v[130:133], v[76:79], v[16:31]
	v_exp_f32_e32 v60, v60
	v_exp_f32_e32 v61, v61
	v_exp_f32_e32 v62, v62
	v_exp_f32_e32 v63, v63
	s_waitcnt vmcnt(2) lgkmcnt(0)
	s_barrier
;   #define RESC() do{}while(0)
;   #define ROT() do{sl_prev=sl_cur;sl_cur=sl_next;sl_next=(sl_next==(NSLOT-1)*SLOTB)?0:sl_next+SLOTB;}while(0)
;   #define ENDW(tt) do{ if((tt)+3<NT){WAIT_BAR(2);} else if((tt)+2<NT){WAIT_BAR(1);} else {WAIT_BAR(0);} }while(0)
; template<int THRL> __device__ __forceinline__ void attn_unit(int b,int h,int qb,const bf16*Q,const bf16*__restrict__ K,const bf16*__restrict__ V,bf16*O,float*gssrow,float mref,char*shm){
;     ...
;   for(;t+1<NT;t+=2){
;     STEP(pB0,pB1,pA0,pA1,t,(t+3<NT),(t+1<NT),(t+1<NT));       ENDW(t);   RESC(); ROT();
;     STEP(pA0,pA1,pB0,pB1,t+1,(t+4<NT),(t+2<NT),(t+2<NT));     ENDW(t+1); RESC(); ROT();
	s_add_i32 s5, s20, 0x2000
	s_cmpk_lg_i32 s20, 0x4000
	s_cselect_b32 s21, s5, 0
	v_add_u32_e32 v175, s29, v199
	ds_read_b64_tr_b16 v[84:85], v175 offset:24576
	ds_read_b64_tr_b16 v[86:87], v175 offset:25088
	v_add_f32_e32 v68, v112, v113
	v_add_f32_e32 v68, v114, v68
	v_add_f32_e32 v68, v115, v68
	v_add_f32_e32 v68, v116, v68
	v_add_f32_e32 v68, v117, v68
	v_cvt_pk_bf16_f32 v154, v112, v113
	v_cvt_pk_bf16_f32 v155, v114, v115
	s_waitcnt lgkmcnt(9)
	v_mfma_f32_32x32x16_bf16 v[96:111], v[64:67], v[158:161], v[32:47]
	ds_read_b64_tr_b16 v[112:113], v175 offset:28672
	ds_read_b64_tr_b16 v[114:115], v175 offset:29184
	v_add_f32_e32 v64, v118, v68
	v_add_f32_e32 v64, v119, v64
	v_add_f32_e32 v64, v120, v64
	v_add_f32_e32 v130, v121, v64
	v_cvt_pk_bf16_f32 v156, v116, v117
	v_cvt_pk_bf16_f32 v157, v118, v119
	s_waitcnt lgkmcnt(10)
	v_mfma_f32_32x32x16_bf16 v[64:79], v[88:91], v[158:161], v[32:47]
	ds_read_b64_tr_b16 v[88:89], v175 offset:25600
	ds_read_b64_tr_b16 v[90:91], v175 offset:26112
	s_waitcnt lgkmcnt(11)
	v_mfma_f32_32x32x16_bf16 v[96:111], v[92:95], v[150:153], v[96:111]
	v_add_f32_e32 v92, v122, v130
	v_add_f32_e32 v92, v123, v92
	v_add_f32_e32 v92, v124, v92
	v_add_f32_e32 v116, v125, v92
	v_cvt_pk_bf16_f32 v146, v120, v121
	v_cvt_pk_bf16_f32 v147, v122, v123
	ds_read_b64_tr_b16 v[92:93], v175 offset:29696
	ds_read_b64_tr_b16 v[94:95], v175 offset:30208
	v_add_f32_e32 v116, v126, v116
	v_add_f32_e32 v116, v127, v116
	v_add_f32_e32 v116, v48, v116
	v_add_f32_e32 v120, v49, v116
	v_cvt_pk_bf16_f32 v148, v124, v125
	v_cvt_pk_bf16_f32 v149, v126, v127
	s_waitcnt lgkmcnt(12)
	v_mfma_f32_32x32x16_bf16 v[64:79], v[162:165], v[150:153], v[64:79]
	ds_read_b64_tr_b16 v[116:117], v175 offset:26624
	ds_read_b64_tr_b16 v[118:119], v175 offset:27136
	v_add_f32_e32 v120, v50, v120
	v_add_f32_e32 v120, v51, v120
	v_add_f32_e32 v120, v52, v120
	v_add_f32_e32 v120, v53, v120
	v_cvt_pk_bf16_f32 v138, v48, v49
	v_cvt_pk_bf16_f32 v139, v50, v51
	s_waitcnt lgkmcnt(13)
	v_mfma_f32_32x32x16_bf16 v[96:111], v[166:169], v[142:145], v[96:111]
	ds_read_b64_tr_b16 v[48:49], v175 offset:30720
	ds_read_b64_tr_b16 v[50:51], v175 offset:31232
	v_add_f32_e32 v120, v54, v120
	v_add_f32_e32 v120, v55, v120
	v_add_f32_e32 v120, v56, v120
	v_add_f32_e32 v120, v57, v120
	v_cvt_pk_bf16_f32 v140, v52, v53
	v_cvt_pk_bf16_f32 v141, v54, v55
	s_waitcnt lgkmcnt(14)
	v_mfma_f32_32x32x16_bf16 v[64:79], v[170:173], v[142:145], v[64:79]
	ds_read_b64_tr_b16 v[52:53], v175 offset:27648
	ds_read_b64_tr_b16 v[54:55], v175 offset:28160
	v_add_f32_e32 v120, v58, v120
	v_add_f32_e32 v120, v59, v120
	v_add_f32_e32 v120, v60, v120
	v_add_f32_e32 v120, v61, v120
	v_cvt_pk_bf16_f32 v130, v56, v57
	v_cvt_pk_bf16_f32 v131, v58, v59
	s_waitcnt lgkmcnt(14)
	v_mfma_f32_32x32x16_bf16 v[96:111], v[188:191], v[134:137], v[96:111]
	ds_read_b64_tr_b16 v[56:57], v175 offset:31744
	ds_read_b64_tr_b16 v[58:59], v175 offset:32256
	v_mfma_f32_32x32x16_bf16 v[64:79], v[80:83], v[134:137], v[64:79]
	v_add_f32_e32 v80, v62, v120
	v_add_f32_e32 v80, v63, v80
	v_add_f32_e32 v80, 0, v80
	v_cvt_pk_bf16_f32 v132, v60, v61
	v_cvt_pk_bf16_f32 v133, v62, v63
	v_lshl_add_u64 v[60:61], v[186:187], 0, s[12:13]
	s_add_i32 s5, s21, s4
	s_mov_b32 s29, m0
	s_mov_b32 m0, s5
	s_nop 0
	global_load_lds_dwordx4 v[60:61], off
	s_mov_b32 m0, s29
	v_add_f32_e32 v174, v174, v80
	s_waitcnt lgkmcnt(14)
	v_mfma_f32_32x32x16_bf16 v[0:15], v[154:157], v[84:87], v[0:15]
	v_exp_f32_e32 v96, v96
	v_exp_f32_e32 v97, v97
	v_exp_f32_e32 v98, v98
	v_exp_f32_e32 v99, v99
	s_waitcnt lgkmcnt(12)
	v_mfma_f32_32x32x16_bf16 v[16:31], v[154:157], v[112:115], v[16:31]
	v_exp_f32_e32 v100, v100
	v_exp_f32_e32 v101, v101
	v_exp_f32_e32 v102, v102
	v_exp_f32_e32 v103, v103
	v_add_u32_e32 v80, s21, v200
	ds_read_b128 v[60:63], v80
	ds_read_b128 v[120:123], v80 offset:512
	s_waitcnt lgkmcnt(12)
	v_mfma_f32_32x32x16_bf16 v[0:15], v[146:149], v[88:91], v[0:15]
	v_exp_f32_e32 v104, v104
	v_exp_f32_e32 v105, v105
	v_exp_f32_e32 v106, v106
	v_exp_f32_e32 v107, v107
	ds_read_b128 v[124:127], v80 offset:2048
	ds_read_b128 v[162:165], v80 offset:2560
	s_waitcnt lgkmcnt(12)
	v_mfma_f32_32x32x16_bf16 v[16:31], v[146:149], v[92:95], v[16:31]
	v_exp_f32_e32 v108, v108
	v_exp_f32_e32 v109, v109
	v_exp_f32_e32 v110, v110
	v_exp_f32_e32 v111, v111
	ds_read_b128 v[166:169], v80 offset:4096
	ds_read_b128 v[170:173], v80 offset:4608
	s_waitcnt lgkmcnt(12)
	v_mfma_f32_32x32x16_bf16 v[0:15], v[138:141], v[116:119], v[0:15]
	v_exp_f32_e32 v64, v64
	v_exp_f32_e32 v65, v65
	v_exp_f32_e32 v66, v66
	v_exp_f32_e32 v67, v67
	ds_read_b128 v[116:119], v80 offset:6144
	ds_read_b128 v[112:115], v80 offset:6656
	s_waitcnt lgkmcnt(12)
	v_mfma_f32_32x32x16_bf16 v[16:31], v[138:141], v[48:51], v[16:31]
	v_exp_f32_e32 v68, v68
	v_exp_f32_e32 v69, v69
	v_exp_f32_e32 v70, v70
	v_exp_f32_e32 v71, v71
	s_waitcnt lgkmcnt(10)
	v_mfma_f32_32x32x16_bf16 v[0:15], v[130:133], v[52:55], v[0:15]
	v_exp_f32_e32 v72, v72
	v_exp_f32_e32 v73, v73
	v_exp_f32_e32 v74, v74
	v_exp_f32_e32 v75, v75
	s_waitcnt lgkmcnt(8)
	v_mfma_f32_32x32x16_bf16 v[16:31], v[130:133], v[56:59], v[16:31]
	v_exp_f32_e32 v76, v76
	v_exp_f32_e32 v77, v77
	v_exp_f32_e32 v78, v78
	v_exp_f32_e32 v79, v79
	s_waitcnt vmcnt(1) lgkmcnt(0)
	s_barrier
;   #define RESC() do{}while(0)
;   #define ROT() do{sl_prev=sl_cur;sl_cur=sl_next;sl_next=(sl_next==(NSLOT-1)*SLOTB)?0:sl_next+SLOTB;}while(0)
;   #define ENDW(tt) do{ if((tt)+3<NT){WAIT_BAR(2);} else if((tt)+2<NT){WAIT_BAR(1);} else {WAIT_BAR(0);} }while(0)
; template<int THRL> __device__ __forceinline__ void attn_unit(int b,int h,int qb,const bf16*Q,const bf16*__restrict__ K,const bf16*__restrict__ V,bf16*O,float*gssrow,float mref,char*shm){
;     ...
;   for(;t+1<NT;t+=2){
;     STEP(pB0,pB1,pA0,pA1,t,(t+3<NT),(t+1<NT),(t+1<NT));       ENDW(t);   RESC(); ROT();
;     STEP(pA0,pA1,pB0,pB1,t+1,(t+4<NT),(t+2<NT),(t+2<NT));     ENDW(t+1); RESC(); ROT();
	s_add_i32 s5, s21, 0x2000
	s_cmpk_lg_i32 s21, 0x4000
	s_cselect_b32 s5, s5, 0
	v_add_u32_e32 v175, s20, v199
	ds_read_b64_tr_b16 v[188:189], v175 offset:24576
	ds_read_b64_tr_b16 v[190:191], v175 offset:25088
	v_add_f32_e32 v48, v96, v97
	v_add_f32_e32 v48, v98, v48
	v_add_f32_e32 v48, v99, v48
	v_add_f32_e32 v48, v100, v48
	v_add_f32_e32 v48, v101, v48
	v_cvt_pk_bf16_f32 v154, v96, v97
	v_cvt_pk_bf16_f32 v155, v98, v99
	s_waitcnt lgkmcnt(9)
	v_mfma_f32_32x32x16_bf16 v[80:95], v[60:63], v[158:161], v[32:47]
	ds_read_b64_tr_b16 v[96:97], v175 offset:28672
	ds_read_b64_tr_b16 v[98:99], v175 offset:29184
	v_add_f32_e32 v48, v102, v48
	v_add_f32_e32 v48, v103, v48
	v_add_f32_e32 v48, v104, v48
	v_add_f32_e32 v130, v105, v48
	s_waitcnt lgkmcnt(10)
	v_mfma_f32_32x32x16_bf16 v[48:63], v[120:123], v[158:161], v[32:47]
	v_cvt_pk_bf16_f32 v156, v100, v101
	v_cvt_pk_bf16_f32 v157, v102, v103
	ds_read_b64_tr_b16 v[120:121], v175 offset:25600
	ds_read_b64_tr_b16 v[122:123], v175 offset:26112
	v_add_f32_e32 v100, v106, v130
	v_add_f32_e32 v100, v107, v100
	v_add_f32_e32 v100, v108, v100
	v_add_f32_e32 v100, v109, v100
	v_cvt_pk_bf16_f32 v146, v104, v105
	v_cvt_pk_bf16_f32 v147, v106, v107
	s_waitcnt lgkmcnt(11)
	v_mfma_f32_32x32x16_bf16 v[80:95], v[124:127], v[150:153], v[80:95]
	ds_read_b64_tr_b16 v[102:103], v175 offset:29696
	ds_read_b64_tr_b16 v[104:105], v175 offset:30208
	s_waitcnt lgkmcnt(12)
	v_mfma_f32_32x32x16_bf16 v[48:63], v[162:165], v[150:153], v[48:63]
	v_add_f32_e32 v100, v110, v100
	v_add_f32_e32 v100, v111, v100
	v_add_f32_e32 v100, v64, v100
	v_add_f32_e32 v100, v65, v100
	v_cvt_pk_bf16_f32 v148, v108, v109
	v_cvt_pk_bf16_f32 v149, v110, v111
	ds_read_b64_tr_b16 v[106:107], v175 offset:26624
	ds_read_b64_tr_b16 v[108:109], v175 offset:27136
	v_add_f32_e32 v100, v66, v100
	v_add_f32_e32 v100, v67, v100
	v_add_f32_e32 v100, v68, v100
	v_add_f32_e32 v100, v69, v100
	v_cvt_pk_bf16_f32 v138, v64, v65
	v_cvt_pk_bf16_f32 v139, v66, v67
	s_waitcnt lgkmcnt(13)
	v_mfma_f32_32x32x16_bf16 v[80:95], v[166:169], v[142:145], v[80:95]
	ds_read_b64_tr_b16 v[64:65], v175 offset:30720
	ds_read_b64_tr_b16 v[66:67], v175 offset:31232
	s_waitcnt lgkmcnt(14)
	v_mfma_f32_32x32x16_bf16 v[48:63], v[170:173], v[142:145], v[48:63]
	v_add_f32_e32 v100, v70, v100
	v_add_f32_e32 v100, v71, v100
	v_add_f32_e32 v100, v72, v100
	v_add_f32_e32 v100, v73, v100
	v_cvt_pk_bf16_f32 v140, v68, v69
	v_cvt_pk_bf16_f32 v141, v70, v71
	ds_read_b64_tr_b16 v[68:69], v175 offset:27648
	ds_read_b64_tr_b16 v[70:71], v175 offset:28160
	v_add_f32_e32 v100, v74, v100
	v_add_f32_e32 v100, v75, v100
	v_add_f32_e32 v100, v76, v100
	v_add_f32_e32 v100, v77, v100
	v_cvt_pk_bf16_f32 v130, v72, v73
	v_cvt_pk_bf16_f32 v131, v74, v75
	s_waitcnt lgkmcnt(14)
	v_mfma_f32_32x32x16_bf16 v[80:95], v[116:119], v[134:137], v[80:95]
	ds_read_b64_tr_b16 v[72:73], v175 offset:31744
	ds_read_b64_tr_b16 v[74:75], v175 offset:32256
	v_mfma_f32_32x32x16_bf16 v[48:63], v[112:115], v[134:137], v[48:63]
	v_add_f32_e32 v100, v78, v100
	v_add_f32_e32 v100, v79, v100
	v_add_f32_e32 v100, 0, v100
	v_cvt_pk_bf16_f32 v132, v76, v77
	v_cvt_pk_bf16_f32 v133, v78, v79
	s_add_i32 s4, s5, s4
	v_lshl_add_u64 v[76:77], v[186:187], 0, s[48:49]
	s_mov_b32 s20, m0
	s_mov_b32 m0, s4
	s_nop 0
	global_load_lds_dwordx4 v[76:77], off
	s_mov_b32 m0, s20
	v_add_f32_e32 v100, v174, v100
	s_waitcnt lgkmcnt(14)
	v_mfma_f32_32x32x16_bf16 v[0:15], v[154:157], v[188:191], v[0:15]
	v_exp_f32_e32 v80, v80
	v_exp_f32_e32 v81, v81
	v_exp_f32_e32 v82, v82
	v_exp_f32_e32 v83, v83
	s_waitcnt lgkmcnt(12)
	v_mfma_f32_32x32x16_bf16 v[16:31], v[154:157], v[96:99], v[16:31]
	v_exp_f32_e32 v84, v84
	v_exp_f32_e32 v85, v85
	v_exp_f32_e32 v86, v86
	v_exp_f32_e32 v87, v87
	v_add_u32_e32 v76, s5, v200
	ds_read_b128 v[110:113], v76
	ds_read_b128 v[114:117], v76 offset:512
	s_waitcnt lgkmcnt(12)
	v_mfma_f32_32x32x16_bf16 v[0:15], v[146:149], v[120:123], v[0:15]
	v_exp_f32_e32 v88, v88
	v_exp_f32_e32 v89, v89
	v_exp_f32_e32 v90, v90
	v_exp_f32_e32 v91, v91
	ds_read_b128 v[118:121], v76 offset:2048
	ds_read_b128 v[122:125], v76 offset:2560
	s_waitcnt lgkmcnt(12)
	v_mfma_f32_32x32x16_bf16 v[16:31], v[146:149], v[102:105], v[16:31]
	v_exp_f32_e32 v92, v92
	v_exp_f32_e32 v93, v93
	v_exp_f32_e32 v94, v94
	v_exp_f32_e32 v95, v95
	ds_read_b128 v[102:105], v76 offset:4096
	ds_read_b128 v[162:165], v76 offset:4608
	s_waitcnt lgkmcnt(12)
	v_mfma_f32_32x32x16_bf16 v[0:15], v[138:141], v[106:109], v[0:15]
	v_exp_f32_e32 v48, v48
	v_exp_f32_e32 v49, v49
	v_exp_f32_e32 v50, v50
	v_exp_f32_e32 v51, v51
	ds_read_b128 v[106:109], v76 offset:6144
	ds_read_b128 v[96:99], v76 offset:6656
	s_waitcnt lgkmcnt(12)
	v_mfma_f32_32x32x16_bf16 v[16:31], v[138:141], v[64:67], v[16:31]
	v_exp_f32_e32 v52, v52
	v_exp_f32_e32 v53, v53
	v_exp_f32_e32 v54, v54
	v_exp_f32_e32 v55, v55
	s_waitcnt lgkmcnt(10)
	v_mfma_f32_32x32x16_bf16 v[0:15], v[130:133], v[68:71], v[0:15]
	v_exp_f32_e32 v56, v56
	v_exp_f32_e32 v57, v57
	v_exp_f32_e32 v58, v58
	v_exp_f32_e32 v59, v59
	s_waitcnt lgkmcnt(8)
	v_mfma_f32_32x32x16_bf16 v[16:31], v[130:133], v[72:75], v[16:31]
	v_exp_f32_e32 v60, v60
	v_exp_f32_e32 v61, v61
	v_exp_f32_e32 v62, v62
	v_exp_f32_e32 v63, v63
	s_waitcnt vmcnt(0) lgkmcnt(0)
	s_barrier
; #define SBAR() __builtin_amdgcn_sched_barrier(0)
;   #define RESC() do{}while(0)
;   #define PKW(P,B) cvtpk_s(P[B],P[B+1])
; template<int THRL> __device__ __forceinline__ void attn_unit(int b,int h,int qb,const bf16*Q,const bf16*__restrict__ K,const bf16*__restrict__ V,bf16*O,float*gssrow,float mref,char*shm){
;     ...
;   STEP(pB0,pB1,pA0,pA1,NT-1,false,false,false); RESC();
;   { float sacc=pB0[0]+pB0[1]; _Pragma("unroll") for(int r=2;r<16;++r)sacc+=pB0[r]; _Pragma("unroll") for(int r=0;r<16;++r)sacc+=pB1[r]; l_reg+=sacc;
;     pw0=(u32x4){PKW(pB0,0),PKW(pB0,2),PKW(pB0,4),PKW(pB0,6)};pw1=(u32x4){PKW(pB0,8),PKW(pB0,10),PKW(pB0,12),PKW(pB0,14)};pw2=(u32x4){PKW(pB1,0),PKW(pB1,2),PKW(pB1,4),PKW(pB1,6)};pw3=(u32x4){PKW(pB1,8),PKW(pB1,10),PKW(pB1,12),PKW(pB1,14)};
;     SBAR(); pv(o,vb0+sl_cur,PAF(0),PAF(1),PAF(2),PAF(3)); }
	v_add_u32_e32 v101, s21, v199
	ds_read_b64_tr_b16 v[166:167], v101 offset:24576
	ds_read_b64_tr_b16 v[168:169], v101 offset:25088
	v_add_f32_e32 v64, v80, v81
	v_add_f32_e32 v64, v82, v64
	v_add_f32_e32 v64, v83, v64
	v_add_f32_e32 v64, v84, v64
	v_add_f32_e32 v126, v85, v64
	v_cvt_pk_bf16_f32 v154, v80, v81
	v_cvt_pk_bf16_f32 v155, v82, v83
	s_waitcnt lgkmcnt(9)
	v_mfma_f32_32x32x16_bf16 v[64:79], v[110:113], v[158:161], v[32:47]
	ds_read_b64_tr_b16 v[80:81], v101 offset:28672
	ds_read_b64_tr_b16 v[82:83], v101 offset:29184
	s_waitcnt lgkmcnt(10)
	v_mfma_f32_32x32x16_bf16 v[32:47], v[114:117], v[158:161], v[32:47]
	v_add_f32_e32 v110, v86, v126
	v_add_f32_e32 v110, v87, v110
	v_add_f32_e32 v110, v88, v110
	v_add_f32_e32 v110, v89, v110
	v_cvt_pk_bf16_f32 v156, v84, v85
	v_cvt_pk_bf16_f32 v157, v86, v87
	ds_read_b64_tr_b16 v[84:85], v101 offset:25600
	ds_read_b64_tr_b16 v[86:87], v101 offset:26112
	v_add_f32_e32 v110, v90, v110
	v_add_f32_e32 v110, v91, v110
	v_add_f32_e32 v110, v92, v110
	v_add_f32_e32 v110, v93, v110
	v_cvt_pk_bf16_f32 v146, v88, v89
	v_cvt_pk_bf16_f32 v147, v90, v91
	s_waitcnt lgkmcnt(11)
	v_mfma_f32_32x32x16_bf16 v[64:79], v[118:121], v[150:153], v[64:79]
	ds_read_b64_tr_b16 v[88:89], v101 offset:29696
	ds_read_b64_tr_b16 v[90:91], v101 offset:30208
	s_waitcnt lgkmcnt(12)
	v_mfma_f32_32x32x16_bf16 v[32:47], v[122:125], v[150:153], v[32:47]
	v_add_f32_e32 v110, v94, v110
	v_add_f32_e32 v110, v95, v110
	v_add_f32_e32 v110, v48, v110
	v_add_f32_e32 v110, v49, v110
	v_cvt_pk_bf16_f32 v148, v92, v93
	v_cvt_pk_bf16_f32 v149, v94, v95
	ds_read_b64_tr_b16 v[92:93], v101 offset:26624
	ds_read_b64_tr_b16 v[94:95], v101 offset:27136
	s_waitcnt lgkmcnt(13)
	v_mfma_f32_32x32x16_bf16 v[64:79], v[102:105], v[142:145], v[64:79]
	v_add_f32_e32 v102, v50, v110
	v_add_f32_e32 v102, v51, v102
	v_add_f32_e32 v102, v52, v102
	v_add_f32_e32 v102, v53, v102
	v_cvt_pk_bf16_f32 v138, v48, v49
	v_cvt_pk_bf16_f32 v139, v50, v51
	ds_read_b64_tr_b16 v[48:49], v101 offset:30720
	ds_read_b64_tr_b16 v[50:51], v101 offset:31232
	s_waitcnt lgkmcnt(14)
	v_mfma_f32_32x32x16_bf16 v[32:47], v[162:165], v[142:145], v[32:47]
	v_add_f32_e32 v102, v54, v102
	v_add_f32_e32 v102, v55, v102
	v_add_f32_e32 v102, v56, v102
	v_add_f32_e32 v102, v57, v102
	v_cvt_pk_bf16_f32 v140, v52, v53
	v_cvt_pk_bf16_f32 v141, v54, v55
	ds_read_b64_tr_b16 v[52:53], v101 offset:27648
	ds_read_b64_tr_b16 v[54:55], v101 offset:28160
	v_add_f32_e32 v102, v58, v102
	v_add_f32_e32 v102, v59, v102
	v_add_f32_e32 v102, v60, v102
	v_add_f32_e32 v102, v61, v102
	v_cvt_pk_bf16_f32 v130, v56, v57
	v_cvt_pk_bf16_f32 v131, v58, v59
	s_waitcnt lgkmcnt(14)
	v_mfma_f32_32x32x16_bf16 v[64:79], v[106:109], v[134:137], v[64:79]
	ds_read_b64_tr_b16 v[56:57], v101 offset:31744
	ds_read_b64_tr_b16 v[58:59], v101 offset:32256
	v_mfma_f32_32x32x16_bf16 v[32:47], v[96:99], v[134:137], v[32:47]
	v_add_f32_e32 v96, v62, v102
	v_add_f32_e32 v96, v63, v96
	v_add_f32_e32 v96, 0, v96
	v_cvt_pk_bf16_f32 v132, v60, v61
	v_cvt_pk_bf16_f32 v133, v62, v63
	s_waitcnt lgkmcnt(14)
	v_mfma_f32_32x32x16_bf16 v[0:15], v[154:157], v[166:169], v[0:15]
	s_nop 1
	v_exp_f32_e32 v64, v64
	v_exp_f32_e32 v65, v65
	v_exp_f32_e32 v66, v66
	v_exp_f32_e32 v67, v67
	s_waitcnt lgkmcnt(12)
	v_mfma_f32_32x32x16_bf16 v[16:31], v[154:157], v[80:83], v[16:31]
	v_exp_f32_e32 v68, v68
	v_exp_f32_e32 v69, v69
	v_exp_f32_e32 v70, v70
	v_exp_f32_e32 v71, v71
	s_waitcnt lgkmcnt(10)
	v_mfma_f32_32x32x16_bf16 v[0:15], v[146:149], v[84:87], v[0:15]
	v_exp_f32_e32 v72, v72
	v_exp_f32_e32 v73, v73
	v_exp_f32_e32 v74, v74
	v_exp_f32_e32 v75, v75
	s_waitcnt lgkmcnt(8)
	v_mfma_f32_32x32x16_bf16 v[16:31], v[146:149], v[88:91], v[16:31]
	v_exp_f32_e32 v76, v76
	v_exp_f32_e32 v77, v77
	v_exp_f32_e32 v78, v78
	v_exp_f32_e32 v79, v79
	s_waitcnt lgkmcnt(6)
	v_mfma_f32_32x32x16_bf16 v[0:15], v[138:141], v[92:95], v[0:15]
	v_exp_f32_e32 v32, v32
	v_exp_f32_e32 v33, v33
	v_exp_f32_e32 v34, v34
	v_exp_f32_e32 v35, v35
	s_waitcnt lgkmcnt(4)
	v_mfma_f32_32x32x16_bf16 v[16:31], v[138:141], v[48:51], v[16:31]
	v_exp_f32_e32 v36, v36
	v_exp_f32_e32 v37, v37
	v_exp_f32_e32 v38, v38
	v_exp_f32_e32 v39, v39
	s_waitcnt lgkmcnt(2)
	v_mfma_f32_32x32x16_bf16 v[0:15], v[130:133], v[52:55], v[0:15]
	v_exp_f32_e32 v40, v40
	v_exp_f32_e32 v41, v41
	v_exp_f32_e32 v42, v42
	v_exp_f32_e32 v43, v43
	s_waitcnt lgkmcnt(0)
	v_mfma_f32_32x32x16_bf16 v[16:31], v[130:133], v[56:59], v[16:31]
	v_exp_f32_e32 v44, v44
	v_exp_f32_e32 v45, v45
	v_exp_f32_e32 v46, v46
	v_exp_f32_e32 v47, v47
	v_add_f32_e32 v48, v64, v65
	v_add_f32_e32 v48, v66, v48
	v_add_f32_e32 v48, v67, v48
	v_add_f32_e32 v48, v68, v48
	v_add_f32_e32 v48, v69, v48
	v_add_f32_e32 v48, v70, v48
	v_add_f32_e32 v48, v71, v48
	v_add_f32_e32 v48, v72, v48
	v_add_f32_e32 v48, v73, v48
	v_add_f32_e32 v48, v74, v48
	v_add_f32_e32 v48, v75, v48
	v_add_f32_e32 v48, v76, v48
	v_add_f32_e32 v48, v77, v48
	v_add_f32_e32 v48, v78, v48
	v_add_f32_e32 v48, v79, v48
	v_add_f32_e32 v48, v32, v48
	v_add_f32_e32 v48, v33, v48
	v_add_f32_e32 v48, v34, v48
	v_add_f32_e32 v48, v35, v48
	v_add_f32_e32 v48, v36, v48
	v_add_f32_e32 v48, v37, v48
	v_add_f32_e32 v48, v38, v48
	v_add_f32_e32 v48, v39, v48
	v_add_f32_e32 v48, v40, v48
	v_add_f32_e32 v48, v41, v48
	v_add_f32_e32 v48, v42, v48
	v_add_f32_e32 v48, v43, v48
	v_add_f32_e32 v48, v44, v48
	v_add_f32_e32 v48, v45, v48
	v_add_f32_e32 v48, v46, v48
	v_add_f32_e32 v48, v47, v48
	v_add_f32_e32 v49, v100, v96
	v_add_f32_e32 v48, v49, v48
	v_cvt_pk_bf16_f32 v32, v32, v33
	v_cvt_pk_bf16_f32 v50, v64, v65
	v_cvt_pk_bf16_f32 v51, v66, v67
	v_cvt_pk_bf16_f32 v52, v68, v69
	v_cvt_pk_bf16_f32 v53, v70, v71
	v_cvt_pk_bf16_f32 v54, v72, v73
	v_cvt_pk_bf16_f32 v55, v74, v75
	v_cvt_pk_bf16_f32 v56, v76, v77
	v_cvt_pk_bf16_f32 v57, v78, v79
	v_cvt_pk_bf16_f32 v33, v34, v35
	v_cvt_pk_bf16_f32 v34, v36, v37
	v_cvt_pk_bf16_f32 v35, v38, v39
	v_cvt_pk_bf16_f32 v36, v40, v41
	v_cvt_pk_bf16_f32 v37, v42, v43
	v_cvt_pk_bf16_f32 v38, v44, v45
	v_cvt_pk_bf16_f32 v39, v46, v47
	v_add3_u32 v49, v128, v198, s5
	ds_read_b64_tr_b16 v[40:41],v49 offset:0
	ds_read_b64_tr_b16 v[42:43],v49 offset:512
	ds_read_b64_tr_b16 v[44:45],v49 offset:1024
	ds_read_b64_tr_b16 v[46:47],v49 offset:1536
	ds_read_b64_tr_b16 v[58:59],v49 offset:2048
	ds_read_b64_tr_b16 v[60:61],v49 offset:2560
	ds_read_b64_tr_b16 v[62:63],v49 offset:3072
	ds_read_b64_tr_b16 v[64:65],v49 offset:3584
	s_waitcnt lgkmcnt(0)
; __device__ __forceinline__ int crow(int r,int hi){return (r&3)+8*(r>>2)+4*hi;}
; #define SBAR() __builtin_amdgcn_sched_barrier(0)
; __device__ __forceinline__ void pv(f32x16*o,int vb,bf16x8 pa0,bf16x8 pa1,bf16x8 pa2,bf16x8 pa3){
;   #pragma unroll
;   for(int d0=0;d0<2;++d0){s16x4 lo[4],hi[4];
;     #pragma unroll
;     for(int ks=0;ks<4;++ks){
;       asm volatile("ds_read_b64_tr_b16 %0,%1 offset:%c2":"=&v"(lo[ks]):"v"(vb),"i"(d0*4096+ks*1024):"memory");
;       asm volatile("ds_read_b64_tr_b16 %0,%1 offset:%c2":"=&v"(hi[ks]):"v"(vb),"i"(d0*4096+ks*1024+512):"memory");}
;     asm volatile("s_waitcnt lgkmcnt(0)":::"memory");SBAR();
;     ...
;     o[d0]=__builtin_amdgcn_mfma_f32_32x32x16_bf16(pa0,PK(0),o[d0],0,0,0);
;     o[d0]=__builtin_amdgcn_mfma_f32_32x32x16_bf16(pa1,PK(1),o[d0],0,0,0);
;     o[d0]=__builtin_amdgcn_mfma_f32_32x32x16_bf16(pa2,PK(2),o[d0],0,0,0);
;     o[d0]=__builtin_amdgcn_mfma_f32_32x32x16_bf16(pa3,PK(3),o[d0],0,0,0);
;     ...
;   }
; }
; template<int THRL> __device__ __forceinline__ void attn_unit(int b,int h,int qb,const bf16*Q,const bf16*__restrict__ K,const bf16*__restrict__ V,bf16*O,float*gssrow,float mref,char*shm){
;     ...
;   __builtin_amdgcn_s_setprio(0);
;   {auto rr=__builtin_amdgcn_permlane32_swap(__float_as_uint(l_reg),__float_as_uint(l_reg),false,false);l_reg=__uint_as_float(rr[0])+__uint_as_float(rr[1]);}
;   if(hi==0)wsf[32+r32]=l_reg;asm volatile("s_waitcnt lgkmcnt(0)":::"memory");
;   float rli[16];
;   #pragma unroll
;   for(int r=0;r<16;++r)rli[r]=__builtin_amdgcn_rcpf(wsf[32+crow(r,hi)]);
;   bf16*Ow=O+(rowbase+q0+wid*QBLK)*OP+h*D;
;   { bf16*stg=(bf16*)(shm+LDS_OST)+wid*2048;
;     #pragma unroll
;     for(int r=0;r<16;++r){const int orow=crow(r,hi);
;       #pragma unroll
;       for(int d0=0;d0<2;++d0)stg[orow*64+d0*32+r32]=__float2bfloat16(o[d0][r]*rli[r]);}
	s_nop 0
	v_mfma_f32_32x32x16_bf16 v[0:15], v[50:53], v[40:43], v[0:15]
	ds_read_b64_tr_b16 v[40:41],v49 offset:4096
	ds_read_b64_tr_b16 v[42:43],v49 offset:4608
	v_mfma_f32_32x32x16_bf16 v[0:15], v[54:57], v[44:47], v[0:15]
	ds_read_b64_tr_b16 v[44:45],v49 offset:5120
	ds_read_b64_tr_b16 v[46:47],v49 offset:5632
	v_mfma_f32_32x32x16_bf16 v[0:15], v[32:35], v[58:61], v[0:15]
	ds_read_b64_tr_b16 v[58:59],v49 offset:6144
	ds_read_b64_tr_b16 v[60:61],v49 offset:6656
	v_mfma_f32_32x32x16_bf16 v[0:15], v[36:39], v[62:65], v[0:15]
	ds_read_b64_tr_b16 v[62:63],v49 offset:7168
	ds_read_b64_tr_b16 v[64:65],v49 offset:7680
	s_waitcnt lgkmcnt(0)
	v_mfma_f32_32x32x16_bf16 v[16:31], v[50:53], v[40:43], v[16:31]
	v_mfma_f32_32x32x16_bf16 v[16:31], v[54:57], v[44:47], v[16:31]
	v_mfma_f32_32x32x16_bf16 v[16:31], v[32:35], v[58:61], v[16:31]
	v_mfma_f32_32x32x16_bf16 v[16:31], v[36:39], v[62:65], v[16:31]
	s_setprio 0
	v_mov_b32_e32 v32, v48
	s_nop 1
	v_permlane32_swap_b32_e32 v48, v32
	v_cmp_gt_u32_e32 vcc, 32, v195
	s_and_saveexec_b64 s[4:5], vcc
	v_add_f32_e32 v32, v48, v32
	v_lshl_add_u32 v33, v196, 2, s15
	ds_write_b32 v33, v32 offset:49280
	s_or_b64 exec, exec, s[4:5]
	s_waitcnt lgkmcnt(0)
	v_lshl_add_u32 v40, v197, 4, s15
	ds_read_b128 v[32:35], v40 offset:49280
	ds_read_b128 v[36:39], v40 offset:49312
	s_lshl_b64 s[4:5], s[46:47], 11
	v_readlane_b32 s12, v253, 63
	s_add_u32 s4, s12, s4
	s_waitcnt lgkmcnt(1)
	v_rcp_f32_e32 v41, v32
	v_readlane_b32 s12, v254, 0
	s_addc_u32 s5, s12, s5
	s_lshl_b32 s14, s14, 12
	v_rcp_f32_e32 v42, v33
	v_rcp_f32_e32 v43, v34
	v_rcp_f32_e32 v44, v35
	s_waitcnt lgkmcnt(0)
	v_rcp_f32_e32 v45, v36
	ds_read_b128 v[32:35], v40 offset:49344
	v_rcp_f32_e32 v46, v37
	v_rcp_f32_e32 v47, v38
	v_rcp_f32_e32 v48, v39
	ds_read_b128 v[36:39], v40 offset:49376
	s_add_i32 s14, s14, 0
	v_lshlrev_b32_e32 v40, 9, v197
	v_lshlrev_b32_e32 v49, 1, v196
	v_mul_f32_e32 v0, v0, v41
	v_add3_u32 v40, s14, v40, v49
	v_cvt_pk_bf16_f32 v0, v0, s0
	ds_write_b16 v40, v0 offset:51200
	v_mul_f32_e32 v0, v16, v41
	v_cvt_pk_bf16_f32 v0, v0, s0
	ds_write_b16 v40, v0 offset:51264
	v_mul_f32_e32 v0, v1, v42
	v_cvt_pk_bf16_f32 v0, v0, s0
	ds_write_b16 v40, v0 offset:51328
	v_mul_f32_e32 v0, v17, v42
	v_cvt_pk_bf16_f32 v0, v0, s0
	ds_write_b16 v40, v0 offset:51392
	v_mul_f32_e32 v0, v2, v43
	v_cvt_pk_bf16_f32 v0, v0, s0
	ds_write_b16 v40, v0 offset:51456
	v_mul_f32_e32 v0, v18, v43
	v_cvt_pk_bf16_f32 v0, v0, s0
	ds_write_b16 v40, v0 offset:51520
	v_mul_f32_e32 v0, v3, v44
	v_cvt_pk_bf16_f32 v0, v0, s0
	ds_write_b16 v40, v0 offset:51584
	v_mul_f32_e32 v0, v19, v44
	v_cvt_pk_bf16_f32 v0, v0, s0
	ds_write_b16 v40, v0 offset:51648
	v_mul_f32_e32 v0, v4, v45
	v_cvt_pk_bf16_f32 v0, v0, s0
	ds_write_b16 v40, v0 offset:52224
	v_mul_f32_e32 v0, v20, v45
	v_cvt_pk_bf16_f32 v0, v0, s0
	ds_write_b16 v40, v0 offset:52288
	v_mul_f32_e32 v0, v5, v46
	v_cvt_pk_bf16_f32 v0, v0, s0
	ds_write_b16 v40, v0 offset:52352
	v_mul_f32_e32 v0, v21, v46
	v_cvt_pk_bf16_f32 v0, v0, s0
	ds_write_b16 v40, v0 offset:52416
	v_mul_f32_e32 v0, v6, v47
	v_cvt_pk_bf16_f32 v0, v0, s0
	ds_write_b16 v40, v0 offset:52480
	v_mul_f32_e32 v0, v22, v47
	v_cvt_pk_bf16_f32 v0, v0, s0
	s_waitcnt lgkmcnt(14)
; __device__ __forceinline__ int crow(int r,int hi){return (r&3)+8*(r>>2)+4*hi;}
; template<int THRL> __device__ __forceinline__ void attn_unit(int b,int h,int qb,const bf16*Q,const bf16*__restrict__ K,const bf16*__restrict__ V,bf16*O,float*gssrow,float mref,char*shm){
;     ...
;   { bf16*stg=(bf16*)(shm+LDS_OST)+wid*2048;
;     #pragma unroll
;     for(int r=0;r<16;++r){const int orow=crow(r,hi);
;       #pragma unroll
;       for(int d0=0;d0<2;++d0)stg[orow*64+d0*32+r32]=__float2bfloat16(o[d0][r]*rli[r]);}
;     asm volatile("s_waitcnt lgkmcnt(0)":::"memory");
;     #pragma unroll
;     for(int i=0;i<4;++i){const int row=i*8+(lane>>3),ch=lane&7; const u32x4 v=*(const u32x4*)(stg+row*64+ch*8); ATTN_STORE16(Ow+(long)row*OP+ch*8,v);
;       float ss=0.f;
;       #pragma unroll
;       for(int e=0;e<4;++e){const float lo=__uint_as_float(v[e]<<16),hi_=__uint_as_float(v[e]&0xffff0000u); ss+=lo*lo+hi_*hi_;}
;       ss+=__shfl_xor(ss,1); ss+=__shfl_xor(ss,2); ss+=__shfl_xor(ss,4);
;       if(ch==0)atomicAdd(gssrow+rowbase+q0+wid*QBLK+row,ss);} }
	v_rcp_f32_e32 v32, v32
	ds_write_b16 v40, v0 offset:52544
	v_mul_f32_e32 v0, v7, v48
	v_cvt_pk_bf16_f32 v0, v0, s0
	ds_write_b16 v40, v0 offset:52608
	v_mul_f32_e32 v0, v23, v48
	v_cvt_pk_bf16_f32 v0, v0, s0
	v_rcp_f32_e32 v33, v33
	ds_write_b16 v40, v0 offset:52672
	v_mul_f32_e32 v0, v8, v32
	v_cvt_pk_bf16_f32 v0, v0, s0
	ds_write_b16 v40, v0 offset:53248
	v_mul_f32_e32 v0, v24, v32
	v_cvt_pk_bf16_f32 v0, v0, s0
	v_rcp_f32_e32 v34, v34
	ds_write_b16 v40, v0 offset:53312
	v_mul_f32_e32 v0, v9, v33
	v_cvt_pk_bf16_f32 v0, v0, s0
	ds_write_b16 v40, v0 offset:53376
	v_mul_f32_e32 v0, v25, v33
	v_cvt_pk_bf16_f32 v0, v0, s0
	v_rcp_f32_e32 v35, v35
	ds_write_b16 v40, v0 offset:53440
	v_mul_f32_e32 v0, v10, v34
	v_cvt_pk_bf16_f32 v0, v0, s0
	ds_write_b16 v40, v0 offset:53504
	v_mul_f32_e32 v0, v26, v34
	v_cvt_pk_bf16_f32 v0, v0, s0
	s_waitcnt lgkmcnt(14)
	v_rcp_f32_e32 v36, v36
	ds_write_b16 v40, v0 offset:53568
	v_mul_f32_e32 v0, v11, v35
	v_cvt_pk_bf16_f32 v0, v0, s0
	ds_write_b16 v40, v0 offset:53632
	v_mul_f32_e32 v0, v27, v35
	v_cvt_pk_bf16_f32 v0, v0, s0
	v_rcp_f32_e32 v37, v37
	ds_write_b16 v40, v0 offset:53696
	v_mul_f32_e32 v0, v12, v36
	v_cvt_pk_bf16_f32 v0, v0, s0
	ds_write_b16 v40, v0 offset:54272
	v_mul_f32_e32 v0, v28, v36
	v_cvt_pk_bf16_f32 v0, v0, s0
	v_rcp_f32_e32 v38, v38
	ds_write_b16 v40, v0 offset:54336
	v_mul_f32_e32 v0, v13, v37
	v_cvt_pk_bf16_f32 v0, v0, s0
	ds_write_b16 v40, v0 offset:54400
	v_mul_f32_e32 v0, v29, v37
	v_cvt_pk_bf16_f32 v0, v0, s0
	v_rcp_f32_e32 v39, v39
	ds_write_b16 v40, v0 offset:54464
	v_mul_f32_e32 v0, v14, v38
	v_cvt_pk_bf16_f32 v0, v0, s0
	ds_write_b16 v40, v0 offset:54528
	v_mul_f32_e32 v0, v30, v38
	v_cvt_pk_bf16_f32 v0, v0, s0
	ds_write_b16 v40, v0 offset:54592
	v_mul_f32_e32 v0, v15, v39
	v_cvt_pk_bf16_f32 v0, v0, s0
	ds_write_b16 v40, v0 offset:54656
	v_mul_f32_e32 v0, v31, v39
	v_and_b32_e32 v6, 7, v194
	v_cvt_pk_bf16_f32 v0, v0, s0
	v_lshlrev_b32_e32 v128, 4, v6
	ds_write_b16 v40, v0 offset:54720
	v_lshrrev_b32_e32 v5, 3, v195
	v_add_u32_e32 v7, s14, v128
	s_waitcnt lgkmcnt(0)
	v_lshl_add_u32 v9, v5, 7, v7
	v_and_b32_e32 v3, 64, v230
	ds_read_b128 v[10:13], v9 offset:51200
	v_xor_b32_e32 v2, 1, v230
	v_add_u32_e32 v4, 64, v3
	v_cmp_lt_i32_e32 vcc, v2, v4
	v_xor_b32_e32 v3, 2, v230
	v_xor_b32_e32 v8, 4, v230
	v_cndmask_b32_e32 v2, v230, v2, vcc
	v_cmp_lt_i32_e32 vcc, v3, v4
	s_waitcnt lgkmcnt(0)
	v_and_b32_e32 v9, 0xffff0000, v11
	v_mul_f32_e32 v9, v9, v9
	v_cndmask_b32_e32 v3, v230, v3, vcc
	v_cmp_lt_i32_e32 vcc, v8, v4
	v_lshlrev_b32_e32 v2, 2, v2
	v_lshlrev_b32_e32 v3, 2, v3
	v_cndmask_b32_e32 v4, v230, v8, vcc
	v_and_b32_e32 v8, 0xffff0000, v10
	v_cmp_eq_u32_e32 vcc, 0, v6
	v_lshlrev_b32_e32 v6, 16, v10
	v_mul_f32_e32 v8, v8, v8
	v_fmac_f32_e32 v8, v6, v6
	v_lshlrev_b32_e32 v6, 16, v11
	v_fmac_f32_e32 v9, v6, v6
	v_add_f32_e32 v6, v8, v9
	v_and_b32_e32 v9, 0xffff0000, v12
	v_lshlrev_b32_e32 v8, 16, v12
	v_mul_f32_e32 v9, v9, v9
	v_fmac_f32_e32 v9, v8, v8
	v_add_f32_e32 v6, v9, v6
	v_and_b32_e32 v9, 0xffff0000, v13
	v_lshlrev_b32_e32 v8, 16, v13
	v_mul_f32_e32 v9, v9, v9
	v_fmac_f32_e32 v9, v8, v8
	v_add_f32_e32 v6, v9, v6
	ds_bpermute_b32 v8, v2, v6
	s_add_u32 s4, s4, s44
	s_addc_u32 s5, s5, s45
	v_lshl_add_u64 v[0:1], s[4:5], 0, v[128:129]
	s_lshl_b64 s[4:5], s[42:43], 2
	s_waitcnt lgkmcnt(0)
	v_add_f32_e32 v6, v6, v8
	ds_bpermute_b32 v8, v3, v6
	v_lshlrev_b32_e32 v4, 2, v4
	s_add_u32 s14, s8, s4
	s_addc_u32 s15, s9, s5
	s_lshl_b64 s[4:5], s[34:35], 2
	s_waitcnt lgkmcnt(0)
	v_add_f32_e32 v8, v6, v8
	ds_bpermute_b32 v9, v4, v8
	s_add_u32 s14, s14, s4
	s_addc_u32 s15, s15, s5
	s_lshl_b64 s[4:5], s[40:41], 2
	s_add_u32 s40, s14, s4
	v_lshlrev_b32_e32 v128, 11, v5
	s_addc_u32 s41, s15, s5
	v_lshl_add_u64 v[14:15], v[0:1], 0, v[128:129]
	v_lshlrev_b32_e32 v6, 2, v5
	global_store_dwordx4 v[14:15], v[10:13], off
	s_and_saveexec_b64 s[4:5], vcc
	s_mov_b32 s13, s95
	s_cbranch_execz .LBB0_455
	s_waitcnt lgkmcnt(0)
	v_add_f32_e32 v8, v8, v9
	global_atomic_add_f32 v6, v8, s[40:41]

; #define LAS __attribute__((address_space(3)))
; __global__ void __launch_bounds__(512) mega_fwd(Args args) {
;     extern __shared__ __attribute__((aligned(16))) unsigned char lds_raw[];
;     LAS unsigned char* lds = (LAS unsigned char*)lds_raw;
;     cg::grid_group grid = cg::this_grid();
;     volatile LAS unsigned* MISC = (volatile LAS unsigned*)(lds + 131072);
;     if (threadIdx.x < 16) MISC[threadIdx.x] = 0u;
;     __syncthreads();
;     XcdBarrier xbar = xcd_barrier_post((unsigned*)(args.ws + WS_BAR), MISC + 8);
	.amdhsa_kernel _Z8mega_fwd4Args
		.amdhsa_group_segment_fixed_size 0
		.amdhsa_private_segment_fixed_size 0
		.amdhsa_kernarg_size 416
		.amdhsa_user_sgpr_count 2
		.amdhsa_user_sgpr_dispatch_ptr 0
		.amdhsa_user_sgpr_queue_ptr 0
		.amdhsa_user_sgpr_kernarg_segment_ptr 1
		.amdhsa_user_sgpr_dispatch_id 0
		.amdhsa_user_sgpr_kernarg_preload_length 0
		.amdhsa_user_sgpr_kernarg_preload_offset 0
		.amdhsa_user_sgpr_private_segment_size 0
		.amdhsa_uses_dynamic_stack 0
		.amdhsa_enable_private_segment 0
		.amdhsa_system_sgpr_workgroup_id_x 1
		.amdhsa_system_sgpr_workgroup_id_y 0
		.amdhsa_system_sgpr_workgroup_id_z 0
		.amdhsa_system_sgpr_workgroup_info 0
		.amdhsa_system_vgpr_workitem_id 2
		.amdhsa_next_free_vgpr 256
		.amdhsa_next_free_sgpr 102
		.amdhsa_accum_offset 256
		.amdhsa_reserve_vcc 1
		.amdhsa_float_round_mode_32 0
		.amdhsa_float_round_mode_16_64 0
		.amdhsa_float_denorm_mode_32 3
		.amdhsa_float_denorm_mode_16_64 3
		.amdhsa_dx10_clamp 1
		.amdhsa_ieee_mode 1
		.amdhsa_fp16_overflow 0
		.amdhsa_tg_split 0
		.amdhsa_exception_fp_ieee_invalid_op 0
		.amdhsa_exception_fp_denorm_src 0
		.amdhsa_exception_fp_ieee_div_zero 0
		.amdhsa_exception_fp_ieee_overflow 0
		.amdhsa_exception_fp_ieee_underflow 0
		.amdhsa_exception_fp_ieee_inexact 0
		.amdhsa_exception_int_div_zero 0
	.end_amdhsa_kernel

; #define LAS __attribute__((address_space(3)))
; __global__ void __launch_bounds__(512) mega_fwd(Args args) {
;     extern __shared__ __attribute__((aligned(16))) unsigned char lds_raw[];
;     LAS unsigned char* lds = (LAS unsigned char*)lds_raw;
;     cg::grid_group grid = cg::this_grid();
;     volatile LAS unsigned* MISC = (volatile LAS unsigned*)(lds + 131072);
;     if (threadIdx.x < 16) MISC[threadIdx.x] = 0u;
;     __syncthreads();
;     XcdBarrier xbar = xcd_barrier_post((unsigned*)(args.ws + WS_BAR), MISC + 8);
amdhsa.kernels:
  - .agpr_count:     0
    .args:
      - .offset:         0
        .size:           160
        .value_kind:     by_value
      - .offset:         160
        .size:           4
        .value_kind:     hidden_block_count_x
      - .offset:         164
        .size:           4
        .value_kind:     hidden_block_count_y
      - .offset:         168
        .size:           4
        .value_kind:     hidden_block_count_z
      - .offset:         172
        .size:           2
        .value_kind:     hidden_group_size_x
      - .offset:         174
        .size:           2
        .value_kind:     hidden_group_size_y
      - .offset:         176
        .size:           2
        .value_kind:     hidden_group_size_z
      - .offset:         178
        .size:           2
        .value_kind:     hidden_remainder_x
      - .offset:         180
        .size:           2
        .value_kind:     hidden_remainder_y
      - .offset:         182
        .size:           2
        .value_kind:     hidden_remainder_z
      - .offset:         200
        .size:           8
        .value_kind:     hidden_global_offset_x
      - .offset:         208
        .size:           8
        .value_kind:     hidden_global_offset_y
      - .offset:         216
        .size:           8
        .value_kind:     hidden_global_offset_z
      - .offset:         224
        .size:           2
        .value_kind:     hidden_grid_dims
      - .offset:         248
        .size:           8
        .value_kind:     hidden_multigrid_sync_arg
      - .offset:         280
        .size:           4
        .value_kind:     hidden_dynamic_lds_size
    .group_segment_fixed_size: 0
    .kernarg_segment_align: 8
    .kernarg_segment_size: 416
    .language:       OpenCL C
    .language_version:
      - 2
      - 0
    .max_flat_workgroup_size: 512
    .name:           _Z8mega_fwd4Args
    .private_segment_fixed_size: 0
    .sgpr_count:     108
    .sgpr_spill_count: 220
    .symbol:         _Z8mega_fwd4Args.kd
    .uniform_work_group_size: 1
    .uses_dynamic_stack: false
    .vgpr_count:     256
    .vgpr_spill_count: 0
    .wavefront_size: 64
